# RG-LRU tile loop: premature s_waitcnt vmcnt(0) after the first barrier moved down to the first consumer of the gq loads (hides a global round trip per tile)
# baseline (speedup 1.0000x reference)
; #define LAS __attribute__((address_space(3)))
; __device__ __forceinline__ float fast_exp2(float x) { return __builtin_amdgcn_exp2f(x); }
; __device__ __forceinline__ float sigmoidf_(float x) { return fast_rcp(1.0f + fast_exp2(-x * LOG2E)); }
; __device__ __forceinline__ int crow(int r, int hi) { return (r & 3) + 8 * (r >> 2) + 4 * hi; }
; __device__ __forceinline__ void rglru_unit(const Params& P, int l, int unit, LAS unsigned char* lds, bool dry = false) {
;     ...
;         bf16_t* gp = proj + O_GR + (rowb + t0 + 16 * ss) * XP + 128 * n + 64 * j + sc;
;         unsigned short gq[16];
; #pragma unroll
;         for (int k = 0; k < 16; ++k) gq[k] = gp[(size_t)k * XP];
;         __syncthreads();
;         f32x16 accr = {}, acci = {};
; #pragma unroll
;         for (int s = 0; s < 8; ++s) { const bf16x8 a = *(const LAS bf16x8*)(xc + (32 * tb + r32) * 272 + (16 * s + 8 * hi) * 2);
;             const bf16x8 wr_ = *(const LAS bf16x8*)(WB + (32 * cb + r32) * 272 + (16 * s + 8 * hi) * 2), wi_ = *(const LAS bf16x8*)(WB + (64 + 32 * cb + r32) * 272 + (16 * s + 8 * hi) * 2);
;             accr = __builtin_amdgcn_mfma_f32_32x32x16_bf16(a, wr_, accr, 0, 0, 0); acci = __builtin_amdgcn_mfma_f32_32x32x16_bf16(a, wi_, acci, 0, 0, 0); }
; #pragma unroll
;         for (int r = 0; r < 16; ++r) { const int tok = 32 * tb + crow(r, hi);
;             const float rr = sigmoidf_(accr[r] + br), ii = sigmoidf_(acci[r] + bi);
;             const float la = -rr * sp8; const float a = fast_exp2(la * LOG2E);
;             const float x2 = 2.0f * la;
;             const float em = -x2 * (1.0f + x2 * (0.5f + x2 * (0.16666667f + x2 * (0.041666668f + x2 * (0.0083333338f + x2 * 0.0013888889f)))));
;             const float mult = __builtin_sqrtf(fmaxf(em, 0.f));
;             const float xcv = bf2f(*(const LAS unsigned short*)(xc + tok * 272 + dch * 2));
;             Ab[tok * 64 + 32 * cb + r32] = a; Ub[tok * 64 + 32 * cb + r32] = mult * ii * xcv; }
.LBB0_367:
	v_lshl_add_u64 v[2:3], v[108:109], 0, s[22:23]
	v_add_co_u32_e32 v126, vcc, 0xae00000, v2
	s_add_u32 s22, s22, 0x40000
	s_nop 0
	v_addc_co_u32_e32 v127, vcc, 0, v3, vcc
	v_add_co_u32_e32 v124, vcc, 0xae01000, v2
	s_addc_u32 s23, s23, 0
	s_nop 0
	v_addc_co_u32_e32 v125, vcc, 0, v3, vcc
	v_add_co_u32_e32 v122, vcc, 0xae02000, v2
	s_cmp_lg_u32 s22, 0x400000
	s_nop 0
	v_addc_co_u32_e32 v123, vcc, 0, v3, vcc
	v_add_co_u32_e32 v120, vcc, 0xae03000, v2
	v_add_u32_e32 v110, 0x80, v110
	s_nop 0
	v_addc_co_u32_e32 v121, vcc, 0, v3, vcc
	v_add_co_u32_e32 v118, vcc, 0xae04000, v2
	global_load_ushort v207, v[126:127], off
	global_load_ushort v206, v[126:127], off offset:2048
	global_load_ushort v205, v[124:125], off
	global_load_ushort v204, v[124:125], off offset:2048
	global_load_ushort v203, v[122:123], off
	global_load_ushort v202, v[122:123], off offset:2048
	global_load_ushort v201, v[120:121], off
	global_load_ushort v200, v[120:121], off offset:2048
	v_addc_co_u32_e32 v119, vcc, 0, v3, vcc
	v_add_co_u32_e32 v116, vcc, 0xae05000, v2
	s_nop 1
	v_addc_co_u32_e32 v117, vcc, 0, v3, vcc
	v_add_co_u32_e32 v114, vcc, 0xae06000, v2
	s_nop 1
	v_addc_co_u32_e32 v115, vcc, 0, v3, vcc
	v_add_co_u32_e32 v112, vcc, 0xae07000, v2
	s_nop 1
	v_addc_co_u32_e32 v113, vcc, 0, v3, vcc
	global_load_ushort v199, v[118:119], off
	global_load_ushort v198, v[118:119], off offset:2048
	global_load_ushort v197, v[116:117], off
	global_load_ushort v196, v[116:117], off offset:2048
	global_load_ushort v195, v[114:115], off
	global_load_ushort v194, v[114:115], off offset:2048
	global_load_ushort v111, v[112:113], off
	global_load_ushort v1, v[112:113], off offset:2048
	s_waitcnt lgkmcnt(0)
	s_barrier
	ds_read_b128 v[2:5], v190
	ds_read_b128 v[6:9], v191
	s_waitcnt lgkmcnt(0)
	v_mfma_f32_32x32x16_bf16 v[18:33], v[2:5], v[6:9], 0
	ds_read_b128 v[6:9], v192
	ds_read_b128 v[208:211], v190 offset:32
	ds_read_b128 v[212:215], v191 offset:32
	s_waitcnt lgkmcnt(2)
	v_mfma_f32_32x32x16_bf16 v[2:17], v[2:5], v[6:9], 0
	s_waitcnt lgkmcnt(0)
	v_mfma_f32_32x32x16_bf16 v[18:33], v[208:211], v[212:215], v[18:33]
	ds_read_b128 v[212:215], v192 offset:32
	s_waitcnt lgkmcnt(0)
	v_mfma_f32_32x32x16_bf16 v[2:17], v[208:211], v[212:215], v[2:17]
	ds_read_b128 v[208:211], v190 offset:64
	ds_read_b128 v[212:215], v191 offset:64
	s_waitcnt lgkmcnt(0)
	v_mfma_f32_32x32x16_bf16 v[18:33], v[208:211], v[212:215], v[18:33]
	ds_read_b128 v[212:215], v192 offset:64
	s_waitcnt lgkmcnt(0)
	v_mfma_f32_32x32x16_bf16 v[2:17], v[208:211], v[212:215], v[2:17]
	ds_read_b128 v[208:211], v190 offset:96
	ds_read_b128 v[212:215], v191 offset:96
	s_waitcnt lgkmcnt(0)
	v_mfma_f32_32x32x16_bf16 v[18:33], v[208:211], v[212:215], v[18:33]
	ds_read_b128 v[212:215], v192 offset:96
	s_waitcnt lgkmcnt(0)
	v_mfma_f32_32x32x16_bf16 v[2:17], v[208:211], v[212:215], v[2:17]
	ds_read_b128 v[208:211], v190 offset:128
	ds_read_b128 v[212:215], v191 offset:128
	s_waitcnt lgkmcnt(0)
	v_mfma_f32_32x32x16_bf16 v[18:33], v[208:211], v[212:215], v[18:33]
	ds_read_b128 v[212:215], v192 offset:128
	s_waitcnt lgkmcnt(0)
	v_mfma_f32_32x32x16_bf16 v[2:17], v[208:211], v[212:215], v[2:17]
	ds_read_b128 v[208:211], v190 offset:160
	ds_read_b128 v[212:215], v191 offset:160
	s_waitcnt lgkmcnt(0)
	v_mfma_f32_32x32x16_bf16 v[18:33], v[208:211], v[212:215], v[18:33]
	ds_read_b128 v[212:215], v192 offset:160
	s_waitcnt lgkmcnt(0)
	v_mfma_f32_32x32x16_bf16 v[2:17], v[208:211], v[212:215], v[2:17]
	ds_read_b128 v[208:211], v190 offset:192
	ds_read_b128 v[212:215], v191 offset:192
	s_waitcnt lgkmcnt(0)
	v_mfma_f32_32x32x16_bf16 v[18:33], v[208:211], v[212:215], v[18:33]
	ds_read_b128 v[212:215], v192 offset:192
	s_waitcnt lgkmcnt(0)
	v_mfma_f32_32x32x16_bf16 v[2:17], v[208:211], v[212:215], v[2:17]
	ds_read_b128 v[208:211], v190 offset:224
	ds_read_b128 v[212:215], v191 offset:224
	ds_read_b128 v[226:229], v192 offset:224
	s_waitcnt lgkmcnt(1)
	v_mfma_f32_32x32x16_bf16 v[18:33], v[208:211], v[212:215], v[18:33]
	s_waitcnt lgkmcnt(0)
	v_mfma_f32_32x32x16_bf16 v[2:17], v[208:211], v[226:229], v[2:17]
	s_nop 9
	v_add_f32_e32 v18, v128, v18
	v_mul_f32_e32 v18, 0xbfb8aa3b, v18
	v_exp_f32_e32 v18, v18
	v_add_f32_e32 v19, v128, v19
	v_mul_f32_e32 v19, 0xbfb8aa3b, v19
	v_exp_f32_e32 v19, v19
	v_add_f32_e32 v18, 1.0, v18
	v_rcp_f32_e64 v18, -v18
	v_add_f32_e32 v2, v129, v2
	v_mul_f32_e32 v2, 0xbfb8aa3b, v2
	v_exp_f32_e32 v2, v2
	v_mul_f32_e32 v18, v130, v18
	v_add_f32_e32 v86, v18, v18
	v_fmamk_f32 v87, v86, 0x3ab60b61, v218
	v_fmaak_f32 v87, v86, v87, 0x3d2aaaab
	v_fmaak_f32 v87, v86, v87, 0x3e2aaaab
	v_fma_f32 v87, v86, v87, 0.5
	v_fma_f32 v87, v86, v87, 1.0
	v_mul_f32_e64 v86, v87, -v86
	v_max_f32_e32 v86, 0, v86
	v_mul_f32_e32 v87, 0x4f800000, v86
	v_cmp_gt_f32_e32 vcc, s0, v86
	v_mul_f32_e32 v18, 0x3fb8aa3b, v18
	v_exp_f32_e32 v18, v18
	v_cndmask_b32_e32 v86, v86, v87, vcc
	v_sqrt_f32_e32 v87, v86
	v_add_f32_e32 v2, 1.0, v2
	v_rcp_f32_e32 v2, v2
	v_add_f32_e32 v3, v129, v3
	v_add_u32_e32 v88, -1, v87
	v_fma_f32 v182, -v88, v87, v86
	v_cmp_ge_f32_e64 s[20:21], 0, v182
	v_add_u32_e32 v182, 1, v87
	v_mul_f32_e32 v3, 0xbfb8aa3b, v3
	v_cndmask_b32_e64 v88, v87, v88, s[20:21]
	v_fma_f32 v87, -v182, v87, v86
	v_cmp_lt_f32_e64 s[20:21], 0, v87
	v_exp_f32_e32 v3, v3
	v_add_f32_e32 v4, v129, v4
	v_cndmask_b32_e64 v87, v88, v182, s[20:21]
	v_mul_f32_e32 v88, 0x37800000, v87
	v_cndmask_b32_e32 v87, v87, v88, vcc
	v_cmp_class_f32_e32 vcc, v86, v219
	v_mul_f32_e32 v4, 0xbfb8aa3b, v4
	v_exp_f32_e32 v4, v4
	v_cndmask_b32_e32 v86, v87, v86, vcc
	ds_read_u16 v87, v193
	ds_read_u16 v88, v193 offset:272
	ds_read_u16 v182, v193 offset:544
	ds_read_u16 v183, v193 offset:816
	ds_read_u16 v184, v193 offset:2176
	ds_read_u16 v185, v193 offset:2448
	ds_read_u16 v208, v193 offset:2720
	ds_read_u16 v209, v193 offset:2992
	ds_write_b32 v134, v18 offset:34816
	v_add_f32_e32 v18, 1.0, v19
	v_rcp_f32_e64 v18, -v18
	s_waitcnt lgkmcnt(8)
; #define LAS __attribute__((address_space(3)))
; __device__ __forceinline__ float fast_exp2(float x) { return __builtin_amdgcn_exp2f(x); }
; __device__ __forceinline__ float sigmoidf_(float x) { return fast_rcp(1.0f + fast_exp2(-x * LOG2E)); }
; __device__ __forceinline__ int crow(int r, int hi) { return (r & 3) + 8 * (r >> 2) + 4 * hi; }
; __device__ __forceinline__ void rglru_unit(const Params& P, int l, int unit, LAS unsigned char* lds, bool dry = false) {
;     ...
;         for (int r = 0; r < 16; ++r) { const int tok = 32 * tb + crow(r, hi);
;             const float rr = sigmoidf_(accr[r] + br), ii = sigmoidf_(acci[r] + bi);
;             const float la = -rr * sp8; const float a = fast_exp2(la * LOG2E);
;             const float x2 = 2.0f * la;
;             const float em = -x2 * (1.0f + x2 * (0.5f + x2 * (0.16666667f + x2 * (0.041666668f + x2 * (0.0083333338f + x2 * 0.0013888889f)))));
;             const float mult = __builtin_sqrtf(fmaxf(em, 0.f));
;             const float xcv = bf2f(*(const LAS unsigned short*)(xc + tok * 272 + dch * 2));
;             Ab[tok * 64 + 32 * cb + r32] = a; Ub[tok * 64 + 32 * cb + r32] = mult * ii * xcv; }
	v_lshlrev_b32_e32 v87, 16, v87
	v_mul_f32_e32 v2, v2, v86
	v_mul_f32_e32 v2, v2, v87
	ds_write_b32 v135, v2
	v_add_f32_e32 v2, 1.0, v3
	v_mul_f32_e32 v3, v130, v18
	v_add_f32_e32 v18, v3, v3
	v_fmamk_f32 v19, v18, 0x3ab60b61, v218
	v_fmaak_f32 v19, v18, v19, 0x3d2aaaab
	v_fmaak_f32 v19, v18, v19, 0x3e2aaaab
	v_fma_f32 v19, v18, v19, 0.5
	v_fma_f32 v19, v18, v19, 1.0
	v_mul_f32_e64 v18, v19, -v18
	v_max_f32_e32 v18, 0, v18
	v_mul_f32_e32 v19, 0x4f800000, v18
	v_cmp_gt_f32_e32 vcc, s0, v18
	v_mul_f32_e32 v3, 0x3fb8aa3b, v3
	v_exp_f32_e32 v3, v3
	v_cndmask_b32_e32 v18, v18, v19, vcc
	v_sqrt_f32_e32 v19, v18
	v_rcp_f32_e32 v2, v2
	ds_write_b32 v136, v3 offset:34816
	v_add_u32_e32 v86, -1, v19
	v_fma_f32 v87, -v86, v19, v18
	v_cmp_ge_f32_e64 s[20:21], 0, v87
	v_add_u32_e32 v87, 1, v19
	s_nop 0
	v_cndmask_b32_e64 v86, v19, v86, s[20:21]
	v_fma_f32 v19, -v87, v19, v18
	v_cmp_lt_f32_e64 s[20:21], 0, v19
	s_nop 1
	v_cndmask_b32_e64 v19, v86, v87, s[20:21]
	v_mul_f32_e32 v86, 0x37800000, v19
	v_cndmask_b32_e32 v19, v19, v86, vcc
	v_cmp_class_f32_e32 vcc, v18, v219
	s_nop 1
	v_cndmask_b32_e32 v18, v19, v18, vcc
	v_add_f32_e32 v19, v128, v20
	v_mul_f32_e32 v19, 0xbfb8aa3b, v19
	v_exp_f32_e32 v19, v19
	s_waitcnt lgkmcnt(9)
	v_lshlrev_b32_e32 v20, 16, v88
	v_mul_f32_e32 v2, v2, v18
	v_mul_f32_e32 v2, v2, v20
	v_add_f32_e32 v3, 1.0, v19
	v_rcp_f32_e64 v3, -v3
	ds_write_b32 v137, v2
	v_add_f32_e32 v2, 1.0, v4
	v_rcp_f32_e32 v2, v2
	v_mul_f32_e32 v3, v130, v3
	v_add_f32_e32 v4, v3, v3
	v_fmamk_f32 v18, v4, 0x3ab60b61, v218
	v_fmaak_f32 v18, v4, v18, 0x3d2aaaab
	v_fmaak_f32 v18, v4, v18, 0x3e2aaaab
	v_fma_f32 v18, v4, v18, 0.5
	v_fma_f32 v18, v4, v18, 1.0
	v_mul_f32_e64 v4, v18, -v4
	v_max_f32_e32 v4, 0, v4
	v_mul_f32_e32 v18, 0x4f800000, v4
	v_cmp_gt_f32_e32 vcc, s0, v4
	v_mul_f32_e32 v3, 0x3fb8aa3b, v3
	v_exp_f32_e32 v3, v3
	v_cndmask_b32_e32 v4, v4, v18, vcc
	v_sqrt_f32_e32 v18, v4
	ds_write_b32 v138, v3 offset:34816
	v_add_u32_e32 v19, -1, v18
	v_fma_f32 v20, -v19, v18, v4
	v_cmp_ge_f32_e64 s[20:21], 0, v20
	v_add_u32_e32 v20, 1, v18
	s_nop 0
	v_cndmask_b32_e64 v19, v18, v19, s[20:21]
	v_fma_f32 v18, -v20, v18, v4
	v_cmp_lt_f32_e64 s[20:21], 0, v18
	s_nop 1
	v_cndmask_b32_e64 v18, v19, v20, s[20:21]
	v_mul_f32_e32 v19, 0x37800000, v18
	v_cndmask_b32_e32 v18, v18, v19, vcc
	v_cmp_class_f32_e32 vcc, v4, v219
	s_waitcnt lgkmcnt(10)
	v_lshlrev_b32_e32 v19, 16, v182
	v_cndmask_b32_e32 v4, v18, v4, vcc
	v_add_f32_e32 v18, v128, v21
	v_mul_f32_e32 v18, 0xbfb8aa3b, v18
	v_exp_f32_e32 v18, v18
	v_mul_f32_e32 v2, v2, v4
	v_add_f32_e32 v4, v129, v5
	v_mul_f32_e32 v4, 0xbfb8aa3b, v4
	v_add_f32_e32 v3, 1.0, v18
	v_rcp_f32_e64 v3, -v3
	v_exp_f32_e32 v4, v4
	v_mul_f32_e32 v2, v2, v19
	ds_write_b32 v139, v2
	v_mul_f32_e32 v3, v130, v3
	v_add_f32_e32 v2, 1.0, v4
	v_add_f32_e32 v4, v3, v3
	v_fmamk_f32 v5, v4, 0x3ab60b61, v218
	v_fmaak_f32 v5, v4, v5, 0x3d2aaaab
	v_fmaak_f32 v5, v4, v5, 0x3e2aaaab
	v_fma_f32 v5, v4, v5, 0.5
	v_fma_f32 v5, v4, v5, 1.0
	v_mul_f32_e64 v4, v5, -v4
	v_max_f32_e32 v4, 0, v4
	v_mul_f32_e32 v5, 0x4f800000, v4
	v_cmp_gt_f32_e32 vcc, s0, v4
	v_mul_f32_e32 v3, 0x3fb8aa3b, v3
	v_rcp_f32_e32 v2, v2
	v_cndmask_b32_e32 v4, v4, v5, vcc
	v_sqrt_f32_e32 v5, v4
	v_exp_f32_e32 v3, v3
	v_add_u32_e32 v18, -1, v5
	v_fma_f32 v19, -v18, v5, v4
	v_cmp_ge_f32_e64 s[20:21], 0, v19
	v_add_u32_e32 v19, 1, v5
	ds_write_b32 v140, v3 offset:34816
	v_cndmask_b32_e64 v18, v5, v18, s[20:21]
	v_fma_f32 v5, -v19, v5, v4
	v_cmp_lt_f32_e64 s[20:21], 0, v5
	s_nop 1
	v_cndmask_b32_e64 v5, v18, v19, s[20:21]
	v_mul_f32_e32 v18, 0x37800000, v5
	v_cndmask_b32_e32 v5, v5, v18, vcc
	v_cmp_class_f32_e32 vcc, v4, v219
	s_waitcnt lgkmcnt(11)
	v_lshlrev_b32_e32 v18, 16, v183
	v_cndmask_b32_e32 v4, v5, v4, vcc
	v_add_f32_e32 v5, v128, v22
	v_mul_f32_e32 v5, 0xbfb8aa3b, v5
	v_exp_f32_e32 v5, v5
	v_mul_f32_e32 v2, v2, v4
	v_add_f32_e32 v4, v129, v6
	v_mul_f32_e32 v4, 0xbfb8aa3b, v4
	v_add_f32_e32 v3, 1.0, v5
	v_rcp_f32_e64 v3, -v3
	v_exp_f32_e32 v4, v4
	v_mul_f32_e32 v2, v2, v18
	ds_write_b32 v141, v2
	v_mul_f32_e32 v3, v130, v3
	v_add_f32_e32 v2, 1.0, v4
	v_add_f32_e32 v4, v3, v3
	v_fmamk_f32 v5, v4, 0x3ab60b61, v218
	v_fmaak_f32 v5, v4, v5, 0x3d2aaaab
	v_fmaak_f32 v5, v4, v5, 0x3e2aaaab
	v_fma_f32 v5, v4, v5, 0.5
	v_fma_f32 v5, v4, v5, 1.0
	v_mul_f32_e64 v4, v5, -v4
	v_max_f32_e32 v4, 0, v4
	v_mul_f32_e32 v5, 0x4f800000, v4
	v_cmp_gt_f32_e32 vcc, s0, v4
	v_mul_f32_e32 v3, 0x3fb8aa3b, v3
	v_rcp_f32_e32 v2, v2
	v_cndmask_b32_e32 v4, v4, v5, vcc
	v_sqrt_f32_e32 v5, v4
	v_exp_f32_e32 v3, v3
	v_add_u32_e32 v6, -1, v5
	v_fma_f32 v18, -v6, v5, v4
	v_cmp_ge_f32_e64 s[20:21], 0, v18
	v_add_u32_e32 v18, 1, v5
	ds_write_b32 v142, v3 offset:34816
	v_cndmask_b32_e64 v6, v5, v6, s[20:21]
	v_fma_f32 v5, -v18, v5, v4
	v_cmp_lt_f32_e64 s[20:21], 0, v5
	s_nop 1
	v_cndmask_b32_e64 v5, v6, v18, s[20:21]
	v_mul_f32_e32 v6, 0x37800000, v5
	v_cndmask_b32_e32 v5, v5, v6, vcc
	v_cmp_class_f32_e32 vcc, v4, v219
	s_waitcnt lgkmcnt(12)
	v_lshlrev_b32_e32 v6, 16, v184
	v_cndmask_b32_e32 v4, v5, v4, vcc
	v_add_f32_e32 v5, v128, v23
	v_mul_f32_e32 v5, 0xbfb8aa3b, v5
	v_exp_f32_e32 v5, v5
	v_mul_f32_e32 v2, v2, v4
	v_add_f32_e32 v4, v129, v7
	v_mul_f32_e32 v4, 0xbfb8aa3b, v4
	v_add_f32_e32 v3, 1.0, v5
	v_rcp_f32_e64 v3, -v3
	v_exp_f32_e32 v4, v4
	v_mul_f32_e32 v2, v2, v6
	ds_write_b32 v143, v2
	v_mul_f32_e32 v3, v130, v3
	v_add_f32_e32 v2, 1.0, v4
	v_add_f32_e32 v4, v3, v3
	v_fmamk_f32 v5, v4, 0x3ab60b61, v218
	v_fmaak_f32 v5, v4, v5, 0x3d2aaaab
	v_fmaak_f32 v5, v4, v5, 0x3e2aaaab
	v_fma_f32 v5, v4, v5, 0.5
	v_fma_f32 v5, v4, v5, 1.0
	v_mul_f32_e64 v4, v5, -v4
	v_max_f32_e32 v4, 0, v4
	v_mul_f32_e32 v5, 0x4f800000, v4
	v_cmp_gt_f32_e32 vcc, s0, v4
	v_mul_f32_e32 v3, 0x3fb8aa3b, v3
	v_rcp_f32_e32 v2, v2
	v_cndmask_b32_e32 v4, v4, v5, vcc
	v_sqrt_f32_e32 v5, v4
	v_exp_f32_e32 v3, v3
	v_add_u32_e32 v6, -1, v5
	v_fma_f32 v7, -v6, v5, v4
	v_cmp_ge_f32_e64 s[20:21], 0, v7
	v_add_u32_e32 v7, 1, v5
	ds_write_b32 v144, v3 offset:34816
	v_cndmask_b32_e64 v6, v5, v6, s[20:21]
	v_fma_f32 v5, -v7, v5, v4
	v_cmp_lt_f32_e64 s[20:21], 0, v5
	s_nop 1
	v_cndmask_b32_e64 v5, v6, v7, s[20:21]
	v_mul_f32_e32 v6, 0x37800000, v5
	v_cndmask_b32_e32 v5, v5, v6, vcc
	v_cmp_class_f32_e32 vcc, v4, v219
	s_waitcnt lgkmcnt(13)
; #define LAS __attribute__((address_space(3)))
; __device__ __forceinline__ float fast_exp2(float x) { return __builtin_amdgcn_exp2f(x); }
; __device__ __forceinline__ float sigmoidf_(float x) { return fast_rcp(1.0f + fast_exp2(-x * LOG2E)); }
; __device__ __forceinline__ int crow(int r, int hi) { return (r & 3) + 8 * (r >> 2) + 4 * hi; }
; __device__ __forceinline__ void rglru_unit(const Params& P, int l, int unit, LAS unsigned char* lds, bool dry = false) {
;     ...
;         for (int r = 0; r < 16; ++r) { const int tok = 32 * tb + crow(r, hi);
;             const float rr = sigmoidf_(accr[r] + br), ii = sigmoidf_(acci[r] + bi);
;             const float la = -rr * sp8; const float a = fast_exp2(la * LOG2E);
;             const float x2 = 2.0f * la;
;             const float em = -x2 * (1.0f + x2 * (0.5f + x2 * (0.16666667f + x2 * (0.041666668f + x2 * (0.0083333338f + x2 * 0.0013888889f)))));
;             const float mult = __builtin_sqrtf(fmaxf(em, 0.f));
;             const float xcv = bf2f(*(const LAS unsigned short*)(xc + tok * 272 + dch * 2));
;             Ab[tok * 64 + 32 * cb + r32] = a; Ub[tok * 64 + 32 * cb + r32] = mult * ii * xcv; }
	v_lshlrev_b32_e32 v6, 16, v185
	v_cndmask_b32_e32 v4, v5, v4, vcc
	v_add_f32_e32 v5, v128, v24
	v_mul_f32_e32 v5, 0xbfb8aa3b, v5
	v_exp_f32_e32 v5, v5
	v_mul_f32_e32 v2, v2, v4
	v_add_f32_e32 v4, v129, v8
	v_mul_f32_e32 v4, 0xbfb8aa3b, v4
	v_add_f32_e32 v3, 1.0, v5
	v_rcp_f32_e64 v3, -v3
	v_exp_f32_e32 v4, v4
	v_mul_f32_e32 v2, v2, v6
	ds_write_b32 v145, v2
	v_mul_f32_e32 v3, v130, v3
	v_add_f32_e32 v2, 1.0, v4
	v_add_f32_e32 v4, v3, v3
	v_fmamk_f32 v5, v4, 0x3ab60b61, v218
	v_fmaak_f32 v5, v4, v5, 0x3d2aaaab
	v_fmaak_f32 v5, v4, v5, 0x3e2aaaab
	v_fma_f32 v5, v4, v5, 0.5
	v_fma_f32 v5, v4, v5, 1.0
	v_mul_f32_e64 v4, v5, -v4
	v_max_f32_e32 v4, 0, v4
	v_mul_f32_e32 v5, 0x4f800000, v4
	v_cmp_gt_f32_e32 vcc, s0, v4
	v_mul_f32_e32 v3, 0x3fb8aa3b, v3
	v_rcp_f32_e32 v2, v2
	v_cndmask_b32_e32 v4, v4, v5, vcc
	v_sqrt_f32_e32 v5, v4
	v_exp_f32_e32 v3, v3
	v_add_u32_e32 v6, -1, v5
	v_fma_f32 v7, -v6, v5, v4
	v_cmp_ge_f32_e64 s[20:21], 0, v7
	v_add_u32_e32 v7, 1, v5
	ds_write_b32 v146, v3 offset:34816
	v_cndmask_b32_e64 v6, v5, v6, s[20:21]
	v_fma_f32 v5, -v7, v5, v4
	v_cmp_lt_f32_e64 s[20:21], 0, v5
	s_nop 1
	v_cndmask_b32_e64 v5, v6, v7, s[20:21]
	v_mul_f32_e32 v6, 0x37800000, v5
	v_cndmask_b32_e32 v5, v5, v6, vcc
	v_cmp_class_f32_e32 vcc, v4, v219
	s_waitcnt lgkmcnt(14)
	v_lshlrev_b32_e32 v6, 16, v208
	v_cndmask_b32_e32 v4, v5, v4, vcc
	v_add_f32_e32 v5, v128, v25
	v_mul_f32_e32 v5, 0xbfb8aa3b, v5
	v_exp_f32_e32 v5, v5
	v_mul_f32_e32 v2, v2, v4
	v_add_f32_e32 v4, v129, v9
	v_mul_f32_e32 v4, 0xbfb8aa3b, v4
	v_add_f32_e32 v3, 1.0, v5
	v_rcp_f32_e64 v3, -v3
	v_exp_f32_e32 v4, v4
	v_mul_f32_e32 v2, v2, v6
	ds_write_b32 v147, v2
	v_mul_f32_e32 v3, v130, v3
	v_add_f32_e32 v2, 1.0, v4
	v_add_f32_e32 v4, v3, v3
	v_fmamk_f32 v5, v4, 0x3ab60b61, v218
	v_fmaak_f32 v5, v4, v5, 0x3d2aaaab
	v_fmaak_f32 v5, v4, v5, 0x3e2aaaab
	v_fma_f32 v5, v4, v5, 0.5
	v_fma_f32 v5, v4, v5, 1.0
	v_mul_f32_e64 v4, v5, -v4
	v_max_f32_e32 v4, 0, v4
	v_mul_f32_e32 v5, 0x4f800000, v4
	v_cmp_gt_f32_e32 vcc, s0, v4
	v_mul_f32_e32 v3, 0x3fb8aa3b, v3
	v_rcp_f32_e32 v2, v2
	v_cndmask_b32_e32 v4, v4, v5, vcc
	v_sqrt_f32_e32 v5, v4
	v_exp_f32_e32 v3, v3
	v_add_u32_e32 v6, -1, v5
	v_fma_f32 v7, -v6, v5, v4
	v_cmp_ge_f32_e64 s[20:21], 0, v7
	v_add_u32_e32 v7, 1, v5
	ds_write_b32 v148, v3 offset:34816
	v_cndmask_b32_e64 v6, v5, v6, s[20:21]
	v_fma_f32 v5, -v7, v5, v4
	v_cmp_lt_f32_e64 s[20:21], 0, v5
	s_nop 1
	v_cndmask_b32_e64 v5, v6, v7, s[20:21]
	v_mul_f32_e32 v6, 0x37800000, v5
	v_cndmask_b32_e32 v5, v5, v6, vcc
	v_cmp_class_f32_e32 vcc, v4, v219
	s_waitcnt lgkmcnt(14)
	v_lshlrev_b32_e32 v6, 16, v209
	v_cndmask_b32_e32 v4, v5, v4, vcc
	v_add_f32_e32 v5, v128, v26
	v_mul_f32_e32 v5, 0xbfb8aa3b, v5
	v_exp_f32_e32 v5, v5
	v_mul_f32_e32 v2, v2, v4
	v_add_f32_e32 v4, v129, v10
	v_mul_f32_e32 v4, 0xbfb8aa3b, v4
	v_add_f32_e32 v3, 1.0, v5
	v_rcp_f32_e64 v3, -v3
	v_exp_f32_e32 v4, v4
	v_mul_f32_e32 v2, v2, v6
	ds_write_b32 v149, v2
	v_mul_f32_e32 v3, v130, v3
	v_add_f32_e32 v2, 1.0, v4
	v_add_f32_e32 v4, v3, v3
	v_fmamk_f32 v5, v4, 0x3ab60b61, v218
	v_fmaak_f32 v5, v4, v5, 0x3d2aaaab
	v_fmaak_f32 v5, v4, v5, 0x3e2aaaab
	v_fma_f32 v5, v4, v5, 0.5
	v_fma_f32 v5, v4, v5, 1.0
	v_mul_f32_e64 v4, v5, -v4
	v_max_f32_e32 v4, 0, v4
	v_mul_f32_e32 v5, 0x4f800000, v4
	v_cmp_gt_f32_e32 vcc, s0, v4
	v_mul_f32_e32 v3, 0x3fb8aa3b, v3
	v_rcp_f32_e32 v2, v2
	v_cndmask_b32_e32 v4, v4, v5, vcc
	v_sqrt_f32_e32 v5, v4
	v_exp_f32_e32 v3, v3
	v_add_u32_e32 v6, -1, v5
	v_fma_f32 v7, -v6, v5, v4
	v_cmp_ge_f32_e64 s[20:21], 0, v7
	v_add_u32_e32 v7, 1, v5
	s_nop 0
	v_cndmask_b32_e64 v6, v5, v6, s[20:21]
	v_fma_f32 v5, -v7, v5, v4
	v_cmp_lt_f32_e64 s[20:21], 0, v5
	s_nop 1
	v_cndmask_b32_e64 v5, v6, v7, s[20:21]
	v_mul_f32_e32 v6, 0x37800000, v5
	v_cndmask_b32_e32 v5, v5, v6, vcc
	v_cmp_class_f32_e32 vcc, v4, v219
	ds_read_u16 v6, v193 offset:4352
	ds_read_u16 v7, v193 offset:4624
	ds_read_u16 v8, v193 offset:4896
	ds_read_u16 v9, v193 offset:5168
	ds_read_u16 v10, v193 offset:6528
	ds_read_u16 v18, v193 offset:6800
	ds_read_u16 v19, v193 offset:7072
	ds_read_u16 v20, v193 offset:7344
	v_cndmask_b32_e32 v4, v5, v4, vcc
	v_add_f32_e32 v5, v128, v27
	v_mul_f32_e32 v5, 0xbfb8aa3b, v5
	v_exp_f32_e32 v5, v5
	ds_write_b32 v150, v3 offset:34816
	v_mul_f32_e32 v2, v2, v4
	v_add_f32_e32 v4, v129, v11
	v_add_f32_e32 v3, 1.0, v5
	v_mul_f32_e32 v4, 0xbfb8aa3b, v4
	v_rcp_f32_e64 v3, -v3
	v_exp_f32_e32 v4, v4
	s_waitcnt lgkmcnt(8)
	v_lshlrev_b32_e32 v6, 16, v6
	v_mul_f32_e32 v2, v2, v6
	v_mul_f32_e32 v3, v130, v3
	ds_write_b32 v151, v2
	v_add_f32_e32 v2, 1.0, v4
	v_add_f32_e32 v4, v3, v3
	v_fmamk_f32 v5, v4, 0x3ab60b61, v218
	v_fmaak_f32 v5, v4, v5, 0x3d2aaaab
	v_fmaak_f32 v5, v4, v5, 0x3e2aaaab
	v_fma_f32 v5, v4, v5, 0.5
	v_fma_f32 v5, v4, v5, 1.0
	v_mul_f32_e64 v4, v5, -v4
	v_max_f32_e32 v4, 0, v4
	v_mul_f32_e32 v5, 0x4f800000, v4
	v_cmp_gt_f32_e32 vcc, s0, v4
	v_mul_f32_e32 v3, 0x3fb8aa3b, v3
	v_rcp_f32_e32 v2, v2
	v_cndmask_b32_e32 v4, v4, v5, vcc
	v_sqrt_f32_e32 v5, v4
	v_exp_f32_e32 v3, v3
	v_add_u32_e32 v6, -1, v5
	v_fma_f32 v11, -v6, v5, v4
	v_cmp_ge_f32_e64 s[20:21], 0, v11
	v_add_u32_e32 v11, 1, v5
	ds_write_b32 v152, v3 offset:34816
	v_cndmask_b32_e64 v6, v5, v6, s[20:21]
	v_fma_f32 v5, -v11, v5, v4
	v_cmp_lt_f32_e64 s[20:21], 0, v5
	s_nop 1
	v_cndmask_b32_e64 v5, v6, v11, s[20:21]
	v_mul_f32_e32 v6, 0x37800000, v5
	v_cndmask_b32_e32 v5, v5, v6, vcc
	v_cmp_class_f32_e32 vcc, v4, v219
	s_waitcnt lgkmcnt(9)
; #define LAS __attribute__((address_space(3)))
; __device__ __forceinline__ float fast_exp2(float x) { return __builtin_amdgcn_exp2f(x); }
; __device__ __forceinline__ float sigmoidf_(float x) { return fast_rcp(1.0f + fast_exp2(-x * LOG2E)); }
; __device__ __forceinline__ int crow(int r, int hi) { return (r & 3) + 8 * (r >> 2) + 4 * hi; }
; __device__ __forceinline__ void rglru_unit(const Params& P, int l, int unit, LAS unsigned char* lds, bool dry = false) {
;     ...
;         for (int r = 0; r < 16; ++r) { const int tok = 32 * tb + crow(r, hi);
;             const float rr = sigmoidf_(accr[r] + br), ii = sigmoidf_(acci[r] + bi);
;             const float la = -rr * sp8; const float a = fast_exp2(la * LOG2E);
;             const float x2 = 2.0f * la;
;             const float em = -x2 * (1.0f + x2 * (0.5f + x2 * (0.16666667f + x2 * (0.041666668f + x2 * (0.0083333338f + x2 * 0.0013888889f)))));
;             const float mult = __builtin_sqrtf(fmaxf(em, 0.f));
;             const float xcv = bf2f(*(const LAS unsigned short*)(xc + tok * 272 + dch * 2));
;             Ab[tok * 64 + 32 * cb + r32] = a; Ub[tok * 64 + 32 * cb + r32] = mult * ii * xcv; }
	v_lshlrev_b32_e32 v6, 16, v7
	v_cndmask_b32_e32 v4, v5, v4, vcc
	v_add_f32_e32 v5, v128, v28
	v_mul_f32_e32 v5, 0xbfb8aa3b, v5
	v_exp_f32_e32 v5, v5
	v_mul_f32_e32 v2, v2, v4
	v_add_f32_e32 v4, v129, v12
	v_mul_f32_e32 v4, 0xbfb8aa3b, v4
	v_add_f32_e32 v3, 1.0, v5
	v_rcp_f32_e64 v3, -v3
	v_exp_f32_e32 v4, v4
	v_mul_f32_e32 v2, v2, v6
	ds_write_b32 v153, v2
	v_mul_f32_e32 v3, v130, v3
	v_add_f32_e32 v2, 1.0, v4
	v_add_f32_e32 v4, v3, v3
	v_fmamk_f32 v5, v4, 0x3ab60b61, v218
	v_fmaak_f32 v5, v4, v5, 0x3d2aaaab
	v_fmaak_f32 v5, v4, v5, 0x3e2aaaab
	v_fma_f32 v5, v4, v5, 0.5
	v_fma_f32 v5, v4, v5, 1.0
	v_mul_f32_e64 v4, v5, -v4
	v_max_f32_e32 v4, 0, v4
	v_mul_f32_e32 v5, 0x4f800000, v4
	v_cmp_gt_f32_e32 vcc, s0, v4
	v_mul_f32_e32 v3, 0x3fb8aa3b, v3
	v_rcp_f32_e32 v2, v2
	v_cndmask_b32_e32 v4, v4, v5, vcc
	v_sqrt_f32_e32 v5, v4
	v_exp_f32_e32 v3, v3
	v_add_u32_e32 v6, -1, v5
	v_fma_f32 v7, -v6, v5, v4
	v_cmp_ge_f32_e64 s[20:21], 0, v7
	v_add_u32_e32 v7, 1, v5
	ds_write_b32 v154, v3 offset:34816
	v_cndmask_b32_e64 v6, v5, v6, s[20:21]
	v_fma_f32 v5, -v7, v5, v4
	v_cmp_lt_f32_e64 s[20:21], 0, v5
	s_nop 1
	v_cndmask_b32_e64 v5, v6, v7, s[20:21]
	v_mul_f32_e32 v6, 0x37800000, v5
	v_cndmask_b32_e32 v5, v5, v6, vcc
	v_cmp_class_f32_e32 vcc, v4, v219
	s_waitcnt lgkmcnt(10)
	v_lshlrev_b32_e32 v6, 16, v8
	v_cndmask_b32_e32 v4, v5, v4, vcc
	v_add_f32_e32 v5, v128, v29
	v_mul_f32_e32 v5, 0xbfb8aa3b, v5
	v_exp_f32_e32 v5, v5
	v_mul_f32_e32 v2, v2, v4
	v_add_f32_e32 v4, v129, v13
	v_mul_f32_e32 v4, 0xbfb8aa3b, v4
	v_add_f32_e32 v3, 1.0, v5
	v_rcp_f32_e64 v3, -v3
	v_exp_f32_e32 v4, v4
	v_mul_f32_e32 v2, v2, v6
	ds_write_b32 v155, v2
	v_mul_f32_e32 v3, v130, v3
	v_add_f32_e32 v2, 1.0, v4
	v_add_f32_e32 v4, v3, v3
	v_fmamk_f32 v5, v4, 0x3ab60b61, v218
	v_fmaak_f32 v5, v4, v5, 0x3d2aaaab
	v_fmaak_f32 v5, v4, v5, 0x3e2aaaab
	v_fma_f32 v5, v4, v5, 0.5
	v_fma_f32 v5, v4, v5, 1.0
	v_mul_f32_e64 v4, v5, -v4
	v_max_f32_e32 v4, 0, v4
	v_mul_f32_e32 v5, 0x4f800000, v4
	v_cmp_gt_f32_e32 vcc, s0, v4
	v_mul_f32_e32 v3, 0x3fb8aa3b, v3
	v_rcp_f32_e32 v2, v2
	v_cndmask_b32_e32 v4, v4, v5, vcc
	v_sqrt_f32_e32 v5, v4
	v_exp_f32_e32 v3, v3
	v_add_u32_e32 v6, -1, v5
	v_fma_f32 v7, -v6, v5, v4
	v_cmp_ge_f32_e64 s[20:21], 0, v7
	v_add_u32_e32 v7, 1, v5
	ds_write_b32 v156, v3 offset:34816
	v_cndmask_b32_e64 v6, v5, v6, s[20:21]
	v_fma_f32 v5, -v7, v5, v4
	v_cmp_lt_f32_e64 s[20:21], 0, v5
	s_nop 1
	v_cndmask_b32_e64 v5, v6, v7, s[20:21]
	v_mul_f32_e32 v6, 0x37800000, v5
	v_cndmask_b32_e32 v5, v5, v6, vcc
	v_cmp_class_f32_e32 vcc, v4, v219
	s_waitcnt lgkmcnt(11)
	v_lshlrev_b32_e32 v6, 16, v9
	v_cndmask_b32_e32 v4, v5, v4, vcc
	v_add_f32_e32 v5, v128, v30
	v_mul_f32_e32 v5, 0xbfb8aa3b, v5
	v_exp_f32_e32 v5, v5
	v_mul_f32_e32 v2, v2, v4
	v_add_f32_e32 v4, v129, v14
	v_mul_f32_e32 v4, 0xbfb8aa3b, v4
	v_add_f32_e32 v3, 1.0, v5
	v_rcp_f32_e64 v3, -v3
	v_exp_f32_e32 v4, v4
	v_mul_f32_e32 v2, v2, v6
	ds_write_b32 v157, v2
	v_mul_f32_e32 v3, v130, v3
	v_add_f32_e32 v2, 1.0, v4
	v_add_f32_e32 v4, v3, v3
	v_fmamk_f32 v5, v4, 0x3ab60b61, v218
	v_fmaak_f32 v5, v4, v5, 0x3d2aaaab
	v_fmaak_f32 v5, v4, v5, 0x3e2aaaab
	v_fma_f32 v5, v4, v5, 0.5
	v_fma_f32 v5, v4, v5, 1.0
	v_mul_f32_e64 v4, v5, -v4
	v_max_f32_e32 v4, 0, v4
	v_mul_f32_e32 v5, 0x4f800000, v4
	v_cmp_gt_f32_e32 vcc, s0, v4
	v_mul_f32_e32 v3, 0x3fb8aa3b, v3
	v_rcp_f32_e32 v2, v2
	v_cndmask_b32_e32 v4, v4, v5, vcc
	v_sqrt_f32_e32 v5, v4
	v_exp_f32_e32 v3, v3
	v_add_u32_e32 v6, -1, v5
	v_fma_f32 v7, -v6, v5, v4
	v_cmp_ge_f32_e64 s[20:21], 0, v7
	v_add_u32_e32 v7, 1, v5
	ds_write_b32 v158, v3 offset:34816
	v_cndmask_b32_e64 v6, v5, v6, s[20:21]
	v_fma_f32 v5, -v7, v5, v4
	v_cmp_lt_f32_e64 s[20:21], 0, v5
	s_nop 1
	v_cndmask_b32_e64 v5, v6, v7, s[20:21]
	v_mul_f32_e32 v6, 0x37800000, v5
	v_cndmask_b32_e32 v5, v5, v6, vcc
	v_cmp_class_f32_e32 vcc, v4, v219
	s_waitcnt lgkmcnt(12)
	v_lshlrev_b32_e32 v6, 16, v10
	v_cndmask_b32_e32 v4, v5, v4, vcc
	v_add_f32_e32 v5, v128, v31
	v_mul_f32_e32 v5, 0xbfb8aa3b, v5
	v_exp_f32_e32 v5, v5
	v_mul_f32_e32 v2, v2, v4
	v_add_f32_e32 v4, v129, v15
	v_mul_f32_e32 v4, 0xbfb8aa3b, v4
	v_add_f32_e32 v3, 1.0, v5
	v_rcp_f32_e64 v3, -v3
	v_exp_f32_e32 v4, v4
	v_mul_f32_e32 v2, v2, v6
	ds_write_b32 v159, v2
	v_mul_f32_e32 v3, v130, v3
	v_add_f32_e32 v2, 1.0, v4
	v_add_f32_e32 v4, v3, v3
	v_fmamk_f32 v5, v4, 0x3ab60b61, v218
	v_fmaak_f32 v5, v4, v5, 0x3d2aaaab
	v_fmaak_f32 v5, v4, v5, 0x3e2aaaab
	v_fma_f32 v5, v4, v5, 0.5
	v_fma_f32 v5, v4, v5, 1.0
	v_mul_f32_e64 v4, v5, -v4
	v_max_f32_e32 v4, 0, v4
	v_mul_f32_e32 v5, 0x4f800000, v4
	v_cmp_gt_f32_e32 vcc, s0, v4
	v_mul_f32_e32 v3, 0x3fb8aa3b, v3
	v_rcp_f32_e32 v2, v2
	v_cndmask_b32_e32 v4, v4, v5, vcc
	v_sqrt_f32_e32 v5, v4
	v_exp_f32_e32 v3, v3
	v_add_u32_e32 v6, -1, v5
	v_fma_f32 v7, -v6, v5, v4
	v_cmp_ge_f32_e64 s[20:21], 0, v7
	v_add_u32_e32 v7, 1, v5
	ds_write_b32 v160, v3 offset:34816
	v_cndmask_b32_e64 v6, v5, v6, s[20:21]
	v_fma_f32 v5, -v7, v5, v4
	v_cmp_lt_f32_e64 s[20:21], 0, v5
	s_nop 1
	v_cndmask_b32_e64 v5, v6, v7, s[20:21]
	v_mul_f32_e32 v6, 0x37800000, v5
	v_cndmask_b32_e32 v5, v5, v6, vcc
	v_cmp_class_f32_e32 vcc, v4, v219
	s_waitcnt lgkmcnt(13)
; #define LAS __attribute__((address_space(3)))
; __device__ __forceinline__ float fast_exp2(float x) { return __builtin_amdgcn_exp2f(x); }
; __device__ __forceinline__ float sigmoidf_(float x) { return fast_rcp(1.0f + fast_exp2(-x * LOG2E)); }
; __device__ __forceinline__ int crow(int r, int hi) { return (r & 3) + 8 * (r >> 2) + 4 * hi; }
; __device__ __forceinline__ void rglru_unit(const Params& P, int l, int unit, LAS unsigned char* lds, bool dry = false) {
;     ...
;         for (int r = 0; r < 16; ++r) { const int tok = 32 * tb + crow(r, hi);
;             const float rr = sigmoidf_(accr[r] + br), ii = sigmoidf_(acci[r] + bi);
;             const float la = -rr * sp8; const float a = fast_exp2(la * LOG2E);
;             const float x2 = 2.0f * la;
;             const float em = -x2 * (1.0f + x2 * (0.5f + x2 * (0.16666667f + x2 * (0.041666668f + x2 * (0.0083333338f + x2 * 0.0013888889f)))));
;             const float mult = __builtin_sqrtf(fmaxf(em, 0.f));
;             const float xcv = bf2f(*(const LAS unsigned short*)(xc + tok * 272 + dch * 2));
;             Ab[tok * 64 + 32 * cb + r32] = a; Ub[tok * 64 + 32 * cb + r32] = mult * ii * xcv; }
;         __syncthreads();
;         { const int c = sc, s = ss;
;           float As = 1.f, Hs = 0.f;
; #pragma unroll
;           for (int k = 0; k < 16; ++k) { const float a = Ab[(16 * s + k) * 64 + c], u = Ub[(16 * s + k) * 64 + c]; Hs = a * Hs + u; As *= a; }
;           seg[s * 64 + c] = (f32x2){As, Hs};
;           __syncthreads();
	v_lshlrev_b32_e32 v6, 16, v18
	v_cndmask_b32_e32 v4, v5, v4, vcc
	v_add_f32_e32 v5, v128, v32
	v_mul_f32_e32 v5, 0xbfb8aa3b, v5
	v_exp_f32_e32 v5, v5
	v_mul_f32_e32 v2, v2, v4
	v_add_f32_e32 v4, v129, v16
	v_mul_f32_e32 v4, 0xbfb8aa3b, v4
	v_add_f32_e32 v3, 1.0, v5
	v_rcp_f32_e64 v3, -v3
	v_exp_f32_e32 v4, v4
	v_mul_f32_e32 v2, v2, v6
	ds_write_b32 v161, v2
	v_mul_f32_e32 v3, v130, v3
	v_add_f32_e32 v2, 1.0, v4
	v_add_f32_e32 v4, v3, v3
	v_fmamk_f32 v5, v4, 0x3ab60b61, v218
	v_fmaak_f32 v5, v4, v5, 0x3d2aaaab
	v_fmaak_f32 v5, v4, v5, 0x3e2aaaab
	v_fma_f32 v5, v4, v5, 0.5
	v_fma_f32 v5, v4, v5, 1.0
	v_mul_f32_e64 v4, v5, -v4
	v_max_f32_e32 v4, 0, v4
	v_mul_f32_e32 v5, 0x4f800000, v4
	v_cmp_gt_f32_e32 vcc, s0, v4
	v_mul_f32_e32 v3, 0x3fb8aa3b, v3
	v_rcp_f32_e32 v2, v2
	v_cndmask_b32_e32 v4, v4, v5, vcc
	v_sqrt_f32_e32 v5, v4
	v_exp_f32_e32 v3, v3
	v_add_u32_e32 v6, -1, v5
	v_fma_f32 v7, -v6, v5, v4
	v_cmp_ge_f32_e64 s[20:21], 0, v7
	v_add_u32_e32 v7, 1, v5
	ds_write_b32 v162, v3 offset:34816
	v_cndmask_b32_e64 v6, v5, v6, s[20:21]
	v_fma_f32 v5, -v7, v5, v4
	v_cmp_lt_f32_e64 s[20:21], 0, v5
	s_nop 1
	v_cndmask_b32_e64 v5, v6, v7, s[20:21]
	v_mul_f32_e32 v6, 0x37800000, v5
	v_cndmask_b32_e32 v5, v5, v6, vcc
	v_cmp_class_f32_e32 vcc, v4, v219
	s_waitcnt lgkmcnt(14)
	v_lshlrev_b32_e32 v6, 16, v19
	v_cndmask_b32_e32 v4, v5, v4, vcc
	v_add_f32_e32 v5, v128, v33
	v_mul_f32_e32 v5, 0xbfb8aa3b, v5
	v_exp_f32_e32 v5, v5
	v_mul_f32_e32 v2, v2, v4
	v_add_f32_e32 v4, v129, v17
	v_mul_f32_e32 v4, 0xbfb8aa3b, v4
	v_add_f32_e32 v3, 1.0, v5
	v_rcp_f32_e64 v3, -v3
	v_exp_f32_e32 v4, v4
	v_mul_f32_e32 v2, v2, v6
	ds_write_b32 v163, v2
	v_mul_f32_e32 v3, v130, v3
	v_add_f32_e32 v2, 1.0, v4
	v_add_f32_e32 v4, v3, v3
	v_fmamk_f32 v5, v4, 0x3ab60b61, v218
	v_fmaak_f32 v5, v4, v5, 0x3d2aaaab
	v_fmaak_f32 v5, v4, v5, 0x3e2aaaab
	v_fma_f32 v5, v4, v5, 0.5
	v_fma_f32 v5, v4, v5, 1.0
	v_mul_f32_e64 v4, v5, -v4
	v_max_f32_e32 v4, 0, v4
	v_mul_f32_e32 v5, 0x4f800000, v4
	v_cmp_gt_f32_e32 vcc, s0, v4
	v_rcp_f32_e32 v2, v2
	v_mul_f32_e32 v3, 0x3fb8aa3b, v3
	v_cndmask_b32_e32 v4, v4, v5, vcc
	v_sqrt_f32_e32 v5, v4
	v_exp_f32_e32 v3, v3
	v_add_u32_e32 v6, -1, v5
	v_fma_f32 v7, -v6, v5, v4
	v_cmp_ge_f32_e64 s[20:21], 0, v7
	v_add_u32_e32 v7, 1, v5
	ds_write_b32 v164, v3 offset:34816
	v_cndmask_b32_e64 v6, v5, v6, s[20:21]
	v_fma_f32 v5, -v7, v5, v4
	v_cmp_lt_f32_e64 s[20:21], 0, v5
	s_nop 1
	v_cndmask_b32_e64 v5, v6, v7, s[20:21]
	v_mul_f32_e32 v6, 0x37800000, v5
	v_cndmask_b32_e32 v5, v5, v6, vcc
	v_cmp_class_f32_e32 vcc, v4, v219
	s_nop 1
	v_cndmask_b32_e32 v4, v5, v4, vcc
	s_waitcnt lgkmcnt(14)
	v_lshlrev_b32_e32 v5, 16, v20
	v_mul_f32_e32 v2, v2, v4
	v_mul_f32_e32 v2, v2, v5
	ds_write_b32 v165, v2
	s_waitcnt lgkmcnt(0)
	s_barrier
	ds_read2st64_b32 v[2:3], v133 offset0:136 offset1:137
	ds_read2st64_b32 v[4:5], v133 offset0:138 offset1:139
	ds_read2st64_b32 v[6:7], v133 offset0:140 offset1:141
	ds_read2st64_b32 v[8:9], v133 offset0:142 offset1:143
	ds_read_b32 v10, v166
	ds_read_b32 v11, v167
	ds_read_b32 v12, v168
	ds_read_b32 v13, v169
	ds_read_b32 v14, v170
	ds_read_b32 v15, v171
	ds_read_b32 v16, v172
	ds_read_b32 v18, v173
	s_waitcnt lgkmcnt(7)
	v_fmac_f32_e32 v10, 0, v2
	s_waitcnt lgkmcnt(6)
	v_fmac_f32_e32 v11, v10, v3
	s_waitcnt lgkmcnt(5)
	v_fmac_f32_e32 v12, v11, v4
	s_waitcnt lgkmcnt(4)
	v_fmac_f32_e32 v13, v12, v5
	s_waitcnt lgkmcnt(3)
	v_fmac_f32_e32 v14, v13, v6
	s_waitcnt lgkmcnt(2)
	v_fmac_f32_e32 v15, v14, v7
	s_waitcnt lgkmcnt(1)
	v_fmac_f32_e32 v16, v15, v8
	v_mul_f32_e32 v2, v2, v3
	s_waitcnt lgkmcnt(0)
	v_fmac_f32_e32 v18, v16, v9
	ds_read2st64_b32 v[10:11], v133 offset0:144 offset1:145
	ds_read2st64_b32 v[12:13], v133 offset0:146 offset1:147
	ds_read2st64_b32 v[14:15], v133 offset0:148 offset1:149
	ds_read2st64_b32 v[16:17], v133 offset0:150 offset1:151
	ds_read_b32 v3, v174
	ds_read_b32 v19, v175
	ds_read_b32 v21, v176
	ds_read_b32 v23, v177
	ds_read_b32 v25, v178
	ds_read_b32 v27, v179
	ds_read_b32 v29, v186
	ds_read_b32 v31, v187
	s_waitcnt lgkmcnt(7)
	v_fmac_f32_e32 v3, v18, v10
	v_mov_b32_e32 v32, v4
	v_mov_b32_e32 v33, v11
	v_mov_b32_e32 v18, v5
	v_mul_f32_e32 v4, v2, v4
	s_waitcnt lgkmcnt(6)
	v_pk_fma_f32 v[2:3], v[2:3], v[32:33], v[18:19]
	v_mul_f32_e32 v4, v4, v5
	v_mov_b32_e32 v5, v3
	v_mov_b32_e32 v2, v6
	v_mov_b32_e32 v3, v12
	v_pk_mul_f32 v[18:19], v[4:5], v[2:3]
	v_mov_b32_e32 v6, v7
	v_mov_b32_e32 v20, v7
	v_pk_mul_f32 v[6:7], v[18:19], v[6:7]
	s_waitcnt lgkmcnt(5)
	v_pk_fma_f32 v[2:3], v[4:5], v[2:3], v[20:21]
	v_mov_b32_e32 v4, v8
	v_mov_b32_e32 v2, v6
	v_mov_b32_e32 v5, v13
	v_pk_mul_f32 v[6:7], v[6:7], v[8:9]
	v_mov_b32_e32 v8, v9
	v_mov_b32_e32 v22, v9
	v_pk_mul_f32 v[6:7], v[6:7], v[8:9]
	s_waitcnt lgkmcnt(4)
	v_pk_fma_f32 v[2:3], v[2:3], v[4:5], v[22:23]
	v_mov_b32_e32 v8, v11
	v_mov_b32_e32 v7, v3
	v_mov_b32_e32 v2, v10
	v_mov_b32_e32 v3, v14
	v_pk_mul_f32 v[4:5], v[6:7], v[2:3]
	v_mov_b32_e32 v24, v11
	v_pk_mul_f32 v[4:5], v[4:5], v[8:9]
	s_waitcnt lgkmcnt(3)
	v_pk_fma_f32 v[2:3], v[6:7], v[2:3], v[24:25]
	v_mov_b32_e32 v6, v12
	v_mov_b32_e32 v2, v4
	v_mov_b32_e32 v7, v15
	v_pk_mul_f32 v[4:5], v[4:5], v[12:13]
	v_mov_b32_e32 v8, v13
	v_mov_b32_e32 v26, v13
	v_pk_mul_f32 v[4:5], v[4:5], v[8:9]
	s_waitcnt lgkmcnt(2)
	v_pk_fma_f32 v[2:3], v[2:3], v[6:7], v[26:27]
	v_mov_b32_e32 v8, v15
	v_mov_b32_e32 v5, v3
	v_mov_b32_e32 v2, v14
	v_mov_b32_e32 v3, v16
	v_pk_mul_f32 v[6:7], v[4:5], v[2:3]
	v_mov_b32_e32 v28, v15
	v_pk_mul_f32 v[6:7], v[6:7], v[8:9]
	s_waitcnt lgkmcnt(1)
	v_pk_fma_f32 v[2:3], v[4:5], v[2:3], v[28:29]
	v_pk_mul_f32 v[4:5], v[6:7], v[16:17]
	v_mov_b32_e32 v2, v6
	v_mov_b32_e32 v6, v17
	v_mov_b32_e32 v30, v17
	v_pk_mul_f32 v[4:5], v[4:5], v[6:7]
	s_waitcnt lgkmcnt(0)
	v_pk_fma_f32 v[2:3], v[2:3], v[16:17], v[30:31]
	s_nop 0
	v_mov_b32_e32 v5, v3
	ds_write_b64 v131, v[4:5]
	s_waitcnt lgkmcnt(0)
	s_barrier
; __device__ __forceinline__ unsigned f2bf(float f) { unsigned u = __builtin_bit_cast(unsigned, f); return (u + 0x7fffu + ((u >> 16) & 1u)) >> 16; }
; __device__ __forceinline__ void rglru_unit(const Params& P, int l, int unit, LAS unsigned char* lds, bool dry = false) {
;     ...
;           float hin = carry, hn = carry;
; #pragma unroll
;           for (int s2 = 0; s2 < 8; ++s2) { if (s2 == s) hin = hn; const f32x2 sg = seg[s2 * 64 + c]; hn = sg.x * hn + sg.y; }
;           carry = hn;
;           float h = hin;
; #pragma unroll
;           for (int k = 0; k < 16; ++k) { const float a = Ab[(16 * s + k) * 64 + c], u = Ub[(16 * s + k) * 64 + c]; h = a * h + u;
;               const float gg = bf2f(gq[k]); gp[(size_t)k * XP] = (bf16_t)f2bf(dry ? gg : gg * h); }
	ds_read2st64_b64 v[2:5], v132 offset1:1
	ds_read2st64_b64 v[6:9], v132 offset0:2 offset1:3
	s_waitcnt lgkmcnt(1)
	v_fma_f32 v2, v89, v2, v3
	v_cndmask_b32_e64 v3, v89, v2, s[6:7]
	v_fmac_f32_e32 v5, v4, v2
	v_cndmask_b32_e64 v10, v3, v5, s[8:9]
	s_waitcnt lgkmcnt(0)
	v_fma_f32 v6, v6, v5, v7
	ds_read2st64_b64 v[2:5], v132 offset0:4 offset1:5
	ds_read2st64_b64 v[86:89], v132 offset0:6 offset1:7
	v_cndmask_b32_e64 v7, v10, v6, s[10:11]
	v_fmac_f32_e32 v9, v8, v6
	v_cndmask_b32_e64 v6, v7, v9, s[12:13]
	s_waitcnt lgkmcnt(1)
	v_fma_f32 v2, v2, v9, v3
	v_cndmask_b32_e64 v3, v6, v2, s[14:15]
	v_fmac_f32_e32 v5, v4, v2
	v_cndmask_b32_e64 v2, v3, v5, s[16:17]
	s_waitcnt lgkmcnt(0)
	v_fma_f32 v10, v86, v5, v87
	v_cndmask_b32_e64 v11, v2, v10, s[18:19]
	ds_read2st64_b32 v[2:3], v133 offset0:136 offset1:137
	ds_read2st64_b32 v[4:5], v133 offset0:138 offset1:139
	ds_read2st64_b32 v[6:7], v133 offset0:140 offset1:141
	ds_read2st64_b32 v[8:9], v133 offset0:142 offset1:143
	ds_read_b32 v12, v166
	ds_read_b32 v13, v167
	ds_read_b32 v14, v168
	ds_read_b32 v15, v169
	ds_read_b32 v16, v170
	ds_read_b32 v17, v171
	ds_read_b32 v18, v172
	ds_read_b32 v19, v173
	s_waitcnt lgkmcnt(7)
	v_fmac_f32_e32 v12, v2, v11
	s_waitcnt vmcnt(0)
	v_lshlrev_b32_e32 v1, 16, v1
	v_lshlrev_b32_e32 v2, 16, v207
	v_mul_f32_e32 v2, v12, v2
	v_bfe_u32 v11, v2, 16, 1
	v_add3_u32 v2, v2, v11, s60
	global_store_short_d16_hi v[126:127], v2, off
	s_waitcnt lgkmcnt(0)
	v_fmac_f32_e32 v13, v3, v12
	v_lshlrev_b32_e32 v2, 16, v206
	v_mul_f32_e32 v2, v13, v2
	v_bfe_u32 v3, v2, 16, 1
	v_add3_u32 v2, v2, v3, s60
	global_store_short_d16_hi v[126:127], v2, off offset:2048
	v_fmac_f32_e32 v14, v4, v13
	v_lshlrev_b32_e32 v2, 16, v205
	v_mul_f32_e32 v2, v14, v2
	v_bfe_u32 v3, v2, 16, 1
	v_add3_u32 v2, v2, v3, s60
	global_store_short_d16_hi v[124:125], v2, off
	v_fmac_f32_e32 v15, v5, v14
	v_lshlrev_b32_e32 v2, 16, v204
	v_mul_f32_e32 v2, v15, v2
	v_bfe_u32 v3, v2, 16, 1
	v_add3_u32 v2, v2, v3, s60
	global_store_short_d16_hi v[124:125], v2, off offset:2048
	v_fmac_f32_e32 v16, v6, v15
	v_lshlrev_b32_e32 v2, 16, v203
	v_mul_f32_e32 v2, v16, v2
	v_bfe_u32 v3, v2, 16, 1
	v_add3_u32 v2, v2, v3, s60
	global_store_short_d16_hi v[122:123], v2, off
	v_fmac_f32_e32 v17, v7, v16
	v_lshlrev_b32_e32 v2, 16, v202
	v_mul_f32_e32 v2, v17, v2
	v_bfe_u32 v3, v2, 16, 1
	v_add3_u32 v2, v2, v3, s60
	global_store_short_d16_hi v[122:123], v2, off offset:2048
	v_fmac_f32_e32 v18, v8, v17
	v_lshlrev_b32_e32 v2, 16, v201
	v_mul_f32_e32 v2, v18, v2
	v_bfe_u32 v3, v2, 16, 1
	v_add3_u32 v2, v2, v3, s60
	global_store_short_d16_hi v[120:121], v2, off
	v_fmac_f32_e32 v19, v9, v18
	v_lshlrev_b32_e32 v2, 16, v200
	v_mul_f32_e32 v2, v19, v2
	v_bfe_u32 v3, v2, 16, 1
	v_add3_u32 v2, v2, v3, s60
	global_store_short_d16_hi v[120:121], v2, off offset:2048
	ds_read2st64_b32 v[2:3], v133 offset0:144 offset1:145
	ds_read2st64_b32 v[4:5], v133 offset0:146 offset1:147
	ds_read2st64_b32 v[6:7], v133 offset0:148 offset1:149
	ds_read2st64_b32 v[8:9], v133 offset0:150 offset1:151
	ds_read_b32 v11, v174
	ds_read_b32 v12, v175
	ds_read_b32 v13, v176
	ds_read_b32 v14, v177
	ds_read_b32 v15, v178
	ds_read_b32 v16, v179
	ds_read_b32 v17, v186
	ds_read_b32 v18, v187
	s_waitcnt lgkmcnt(0)
	v_fmac_f32_e32 v11, v19, v2
	v_lshlrev_b32_e32 v2, 16, v199
	v_mul_f32_e32 v2, v11, v2
	v_bfe_u32 v19, v2, 16, 1
	v_add3_u32 v2, v2, v19, s60
	global_store_short_d16_hi v[118:119], v2, off
	v_fmac_f32_e32 v12, v11, v3
	v_lshlrev_b32_e32 v2, 16, v198
	v_mul_f32_e32 v2, v12, v2
	v_bfe_u32 v3, v2, 16, 1
	v_add3_u32 v2, v2, v3, s60
	global_store_short_d16_hi v[118:119], v2, off offset:2048
	v_fmac_f32_e32 v13, v12, v4
	v_lshlrev_b32_e32 v2, 16, v197
	v_mul_f32_e32 v2, v13, v2
	v_bfe_u32 v3, v2, 16, 1
	v_add3_u32 v2, v2, v3, s60
	global_store_short_d16_hi v[116:117], v2, off
	v_fmac_f32_e32 v14, v13, v5
	v_lshlrev_b32_e32 v2, 16, v196
	v_mul_f32_e32 v2, v14, v2
	v_bfe_u32 v3, v2, 16, 1
	v_add3_u32 v2, v2, v3, s60
	global_store_short_d16_hi v[116:117], v2, off offset:2048
	v_fmac_f32_e32 v15, v14, v6
	v_lshlrev_b32_e32 v2, 16, v195
	v_mul_f32_e32 v2, v15, v2
	v_bfe_u32 v3, v2, 16, 1
	v_add3_u32 v2, v2, v3, s60
	global_store_short_d16_hi v[114:115], v2, off
	v_fmac_f32_e32 v16, v15, v7
	v_lshlrev_b32_e32 v2, 16, v194
	v_mul_f32_e32 v2, v16, v2
	v_bfe_u32 v3, v2, 16, 1
	v_add3_u32 v2, v2, v3, s60
	global_store_short_d16_hi v[114:115], v2, off offset:2048
	v_fmac_f32_e32 v17, v16, v8
	v_lshlrev_b32_e32 v2, 16, v111
	v_mul_f32_e32 v2, v17, v2
	v_bfe_u32 v3, v2, 16, 1
	v_fmac_f32_e32 v18, v17, v9
	v_add3_u32 v2, v2, v3, s60
	v_mul_f32_e32 v1, v18, v1
	global_store_short_d16_hi v[112:113], v2, off
	v_bfe_u32 v2, v1, 16, 1
	v_add3_u32 v1, v1, v2, s60
	v_fmac_f32_e32 v89, v88, v10
	global_store_short_d16_hi v[112:113], v1, off offset:2048
	s_cbranch_scc0 .LBB0_346

; __device__ __forceinline__ float fast_rcp(float x) { return __builtin_amdgcn_rcpf(x); }
; __device__ __forceinline__ u32x4 pack8(f32x4 v0, f32x4 v1) { u32x4 w; w.x = cvt_pk_bf16(v0[0], v0[1]); w.y = cvt_pk_bf16(v0[2], v0[3]); w.z = cvt_pk_bf16(v1[0], v1[1]); w.w = cvt_pk_bf16(v1[2], v1[3]); return w; }
;     __device__ __forceinline__ void operator()(f32x4 (&acc)[2][2][4][2], const Unit& u, int seg, int wr, int wc, int fr, int fq) const {
;     ...
;                 for (int bj = 0; bj < 2; ++bj) { const int col = colt + bj * HALF;
;                     const u32x4 aw = *(const u32x4*)(P + gate_frag_off(u.pm, u.pn, wave, ai, m, bj, lane, ga));
;                     f32x4 s0 = {bflo(aw.x), bfhi(aw.x), bflo(aw.y), bfhi(aw.y)}, s1 = {bflo(aw.z), bfhi(aw.z), bflo(aw.w), bfhi(aw.w)};
;                     if (seg != 2) { const u32x4 bw = *(const u32x4*)(P + gate_frag_off(u.pm, u.pn, wave, ai, m, bj, lane, gb));
;                         const f32x4 d0 = {bflo(bw.x), bfhi(bw.x), bflo(bw.y), bfhi(bw.y)}, d1 = {bflo(bw.z), bfhi(bw.z), bflo(bw.w), bfhi(bw.w)};
; #pragma unroll
;                         for (int e = 0; e < 4; ++e) { s0[e] *= fast_rcp(d0[e]); s1[e] *= fast_rcp(d1[e]); } }
;                     acc[ai][bj][m][0] *= s0; acc[ai][bj][m][1] *= s1;
;                     if (seg == 2) *(u32x4*)(Mb + (size_t)row * DM + col) = pack8(acc[ai][bj][m][0], acc[ai][bj][m][1]); }
.Lm3_seg2:
	s_add_u32 s10, s26, 0x10000000
	s_addc_u32 s11, s27, 0
	v_lshl_add_u64 v[142:143], v[140:141], 0, s[10:11]
	global_load_dwordx4 v[162:165], v[142:143], off
	global_load_dwordx4 v[166:169], v[142:143], off offset:1024
	global_load_dwordx4 v[170:173], v[142:143], off offset:2048
	global_load_dwordx4 v[174:177], v[142:143], off offset:3072
	s_mov_b64 vcc, 0x1000
	v_lshl_add_u64 v[142:143], v[142:143], 0, vcc
	global_load_dwordx4 v[182:185], v[142:143], off
	global_load_dwordx4 v[186:189], v[142:143], off offset:1024
	global_load_dwordx4 v[190:193], v[142:143], off offset:2048
	global_load_dwordx4 v[194:197], v[142:143], off offset:3072
	s_mov_b64 vcc, 0x1000
	v_lshl_add_u64 v[142:143], v[142:143], 0, vcc
	global_load_dwordx4 v[198:201], v[142:143], off
	global_load_dwordx4 v[202:205], v[142:143], off offset:1024
	global_load_dwordx4 v[206:209], v[142:143], off offset:2048
	global_load_dwordx4 v[210:213], v[142:143], off offset:3072
	s_mov_b64 vcc, 0x1000
	v_lshl_add_u64 v[142:143], v[142:143], 0, vcc
	global_load_dwordx4 v[226:229], v[142:143], off
	global_load_dwordx4 v[232:235], v[142:143], off offset:1024
	global_load_dwordx4 v[236:239], v[142:143], off offset:2048
	global_load_dwordx4 v[240:243], v[142:143], off offset:3072
	v_lshl_add_u32 v144, s28, 8, v156
	v_lshl_or_b32 v2, s30, 8, v158
	v_lshlrev_b32_e32 v144, 11, v144
	v_lshl_add_u32 v144, v2, 1, v144
	s_waitcnt vmcnt(15)
	v_lshlrev_b32_e32 v146, 16, v162
	v_and_b32_e32 v147, 0xffff0000, v162
	v_lshlrev_b32_e32 v148, 16, v163
	v_and_b32_e32 v149, 0xffff0000, v163
	v_lshlrev_b32_e32 v150, 16, v164
	v_and_b32_e32 v151, 0xffff0000, v164
	v_lshlrev_b32_e32 v152, 16, v165
	v_and_b32_e32 v153, 0xffff0000, v165
	v_pk_mul_f32 v[120:121], v[120:121], v[146:147]
	v_pk_mul_f32 v[122:123], v[122:123], v[148:149]
	v_pk_mul_f32 v[116:117], v[116:117], v[150:151]
	v_pk_mul_f32 v[118:119], v[118:119], v[152:153]
	v_cvt_pk_bf16_f32 v162, v120, v121
	v_cvt_pk_bf16_f32 v163, v122, v123
	v_cvt_pk_bf16_f32 v164, v116, v117
	v_cvt_pk_bf16_f32 v165, v118, v119
	s_mov_b64 s[10:11], s[4:5]
	global_store_dwordx4 v144, v[162:165], s[10:11]
	s_waitcnt vmcnt(15)
	v_lshlrev_b32_e32 v146, 16, v166
	v_and_b32_e32 v147, 0xffff0000, v166
	v_lshlrev_b32_e32 v148, 16, v167
	v_and_b32_e32 v149, 0xffff0000, v167
	v_lshlrev_b32_e32 v150, 16, v168
	v_and_b32_e32 v151, 0xffff0000, v168
	v_lshlrev_b32_e32 v152, 16, v169
	v_and_b32_e32 v153, 0xffff0000, v169
	v_pk_mul_f32 v[88:89], v[88:89], v[146:147]
	v_pk_mul_f32 v[90:91], v[90:91], v[148:149]
	v_pk_mul_f32 v[84:85], v[84:85], v[150:151]
	v_pk_mul_f32 v[86:87], v[86:87], v[152:153]
	v_cvt_pk_bf16_f32 v166, v88, v89
	v_cvt_pk_bf16_f32 v167, v90, v91
	v_cvt_pk_bf16_f32 v168, v84, v85
	v_cvt_pk_bf16_f32 v169, v86, v87
	global_store_dwordx4 v144, v[166:169], s[10:11] offset:256
	s_waitcnt vmcnt(15)
	v_lshlrev_b32_e32 v146, 16, v170
	v_and_b32_e32 v147, 0xffff0000, v170
	v_lshlrev_b32_e32 v148, 16, v171
	v_and_b32_e32 v149, 0xffff0000, v171
	v_lshlrev_b32_e32 v150, 16, v172
	v_and_b32_e32 v151, 0xffff0000, v172
	v_lshlrev_b32_e32 v152, 16, v173
	v_and_b32_e32 v153, 0xffff0000, v173
	v_pk_mul_f32 v[112:113], v[112:113], v[146:147]
	v_pk_mul_f32 v[114:115], v[114:115], v[148:149]
	v_pk_mul_f32 v[108:109], v[108:109], v[150:151]
	v_pk_mul_f32 v[110:111], v[110:111], v[152:153]
	v_cvt_pk_bf16_f32 v170, v112, v113
	v_cvt_pk_bf16_f32 v171, v114, v115
	v_cvt_pk_bf16_f32 v172, v108, v109
	v_cvt_pk_bf16_f32 v173, v110, v111
	s_add_u32 s10, s4, 0x8000
	s_addc_u32 s11, s5, 0
	global_store_dwordx4 v144, v[170:173], s[10:11]
	s_waitcnt vmcnt(15)
	v_lshlrev_b32_e32 v146, 16, v174
	v_and_b32_e32 v147, 0xffff0000, v174
	v_lshlrev_b32_e32 v148, 16, v175
	v_and_b32_e32 v149, 0xffff0000, v175
	v_lshlrev_b32_e32 v150, 16, v176
	v_and_b32_e32 v151, 0xffff0000, v176
	v_lshlrev_b32_e32 v152, 16, v177
	v_and_b32_e32 v153, 0xffff0000, v177
	v_pk_mul_f32 v[80:81], v[80:81], v[146:147]
	v_pk_mul_f32 v[82:83], v[82:83], v[148:149]
	v_pk_mul_f32 v[76:77], v[76:77], v[150:151]
	v_pk_mul_f32 v[78:79], v[78:79], v[152:153]
	v_cvt_pk_bf16_f32 v174, v80, v81
	v_cvt_pk_bf16_f32 v175, v82, v83
	v_cvt_pk_bf16_f32 v176, v76, v77
	v_cvt_pk_bf16_f32 v177, v78, v79
	global_store_dwordx4 v144, v[174:177], s[10:11] offset:256
	s_waitcnt vmcnt(15)
	v_lshlrev_b32_e32 v146, 16, v182
	v_and_b32_e32 v147, 0xffff0000, v182
	v_lshlrev_b32_e32 v148, 16, v183
	v_and_b32_e32 v149, 0xffff0000, v183
	v_lshlrev_b32_e32 v150, 16, v184
	v_and_b32_e32 v151, 0xffff0000, v184
	v_lshlrev_b32_e32 v152, 16, v185
	v_and_b32_e32 v153, 0xffff0000, v185
	v_pk_mul_f32 v[104:105], v[104:105], v[146:147]
	v_pk_mul_f32 v[106:107], v[106:107], v[148:149]
	v_pk_mul_f32 v[100:101], v[100:101], v[150:151]
	v_pk_mul_f32 v[102:103], v[102:103], v[152:153]
	v_cvt_pk_bf16_f32 v182, v104, v105
	v_cvt_pk_bf16_f32 v183, v106, v107
	v_cvt_pk_bf16_f32 v184, v100, v101
	v_cvt_pk_bf16_f32 v185, v102, v103
	s_add_u32 s10, s4, 0x10000
	s_addc_u32 s11, s5, 0
	global_store_dwordx4 v144, v[182:185], s[10:11]
	s_waitcnt vmcnt(15)
	v_lshlrev_b32_e32 v146, 16, v186
	v_and_b32_e32 v147, 0xffff0000, v186
	v_lshlrev_b32_e32 v148, 16, v187
	v_and_b32_e32 v149, 0xffff0000, v187
	v_lshlrev_b32_e32 v150, 16, v188
	v_and_b32_e32 v151, 0xffff0000, v188
	v_lshlrev_b32_e32 v152, 16, v189
	v_and_b32_e32 v153, 0xffff0000, v189
	v_pk_mul_f32 v[72:73], v[72:73], v[146:147]
	v_pk_mul_f32 v[74:75], v[74:75], v[148:149]
	v_pk_mul_f32 v[68:69], v[68:69], v[150:151]
	v_pk_mul_f32 v[70:71], v[70:71], v[152:153]
	v_cvt_pk_bf16_f32 v186, v72, v73
	v_cvt_pk_bf16_f32 v187, v74, v75
	v_cvt_pk_bf16_f32 v188, v68, v69
	v_cvt_pk_bf16_f32 v189, v70, v71
	global_store_dwordx4 v144, v[186:189], s[10:11] offset:256
	s_waitcnt vmcnt(15)
; __device__ __forceinline__ float fast_rcp(float x) { return __builtin_amdgcn_rcpf(x); }
; __device__ __forceinline__ u32x4 pack8(f32x4 v0, f32x4 v1) { u32x4 w; w.x = cvt_pk_bf16(v0[0], v0[1]); w.y = cvt_pk_bf16(v0[2], v0[3]); w.z = cvt_pk_bf16(v1[0], v1[1]); w.w = cvt_pk_bf16(v1[2], v1[3]); return w; }
;     __device__ __forceinline__ void operator()(f32x4 (&acc)[2][2][4][2], const Unit& u, int seg, int wr, int wc, int fr, int fq) const {
;     ...
;                 for (int bj = 0; bj < 2; ++bj) { const int col = colt + bj * HALF;
;                     const u32x4 aw = *(const u32x4*)(P + gate_frag_off(u.pm, u.pn, wave, ai, m, bj, lane, ga));
;                     f32x4 s0 = {bflo(aw.x), bfhi(aw.x), bflo(aw.y), bfhi(aw.y)}, s1 = {bflo(aw.z), bfhi(aw.z), bflo(aw.w), bfhi(aw.w)};
;                     if (seg != 2) { const u32x4 bw = *(const u32x4*)(P + gate_frag_off(u.pm, u.pn, wave, ai, m, bj, lane, gb));
;                         const f32x4 d0 = {bflo(bw.x), bfhi(bw.x), bflo(bw.y), bfhi(bw.y)}, d1 = {bflo(bw.z), bfhi(bw.z), bflo(bw.w), bfhi(bw.w)};
; #pragma unroll
;                         for (int e = 0; e < 4; ++e) { s0[e] *= fast_rcp(d0[e]); s1[e] *= fast_rcp(d1[e]); } }
;                     acc[ai][bj][m][0] *= s0; acc[ai][bj][m][1] *= s1;
;                     if (seg == 2) *(u32x4*)(Mb + (size_t)row * DM + col) = pack8(acc[ai][bj][m][0], acc[ai][bj][m][1]); }
	v_lshlrev_b32_e32 v146, 16, v190
	v_and_b32_e32 v147, 0xffff0000, v190
	v_lshlrev_b32_e32 v148, 16, v191
	v_and_b32_e32 v149, 0xffff0000, v191
	v_lshlrev_b32_e32 v150, 16, v192
	v_and_b32_e32 v151, 0xffff0000, v192
	v_lshlrev_b32_e32 v152, 16, v193
	v_and_b32_e32 v153, 0xffff0000, v193
	v_pk_mul_f32 v[96:97], v[96:97], v[146:147]
	v_pk_mul_f32 v[98:99], v[98:99], v[148:149]
	v_pk_mul_f32 v[92:93], v[92:93], v[150:151]
	v_pk_mul_f32 v[94:95], v[94:95], v[152:153]
	v_cvt_pk_bf16_f32 v190, v96, v97
	v_cvt_pk_bf16_f32 v191, v98, v99
	v_cvt_pk_bf16_f32 v192, v92, v93
	v_cvt_pk_bf16_f32 v193, v94, v95
	s_add_u32 s10, s4, 0x18000
	s_addc_u32 s11, s5, 0
	global_store_dwordx4 v144, v[190:193], s[10:11]
	s_waitcnt vmcnt(15)
	v_lshlrev_b32_e32 v146, 16, v194
	v_and_b32_e32 v147, 0xffff0000, v194
	v_lshlrev_b32_e32 v148, 16, v195
	v_and_b32_e32 v149, 0xffff0000, v195
	v_lshlrev_b32_e32 v150, 16, v196
	v_and_b32_e32 v151, 0xffff0000, v196
	v_lshlrev_b32_e32 v152, 16, v197
	v_and_b32_e32 v153, 0xffff0000, v197
	v_pk_mul_f32 v[64:65], v[64:65], v[146:147]
	v_pk_mul_f32 v[66:67], v[66:67], v[148:149]
	v_pk_mul_f32 v[60:61], v[60:61], v[150:151]
	v_pk_mul_f32 v[62:63], v[62:63], v[152:153]
	v_cvt_pk_bf16_f32 v194, v64, v65
	v_cvt_pk_bf16_f32 v195, v66, v67
	v_cvt_pk_bf16_f32 v196, v60, v61
	v_cvt_pk_bf16_f32 v197, v62, v63
	global_store_dwordx4 v144, v[194:197], s[10:11] offset:256
	s_waitcnt vmcnt(15)
	v_lshlrev_b32_e32 v146, 16, v198
	v_and_b32_e32 v147, 0xffff0000, v198
	v_lshlrev_b32_e32 v148, 16, v199
	v_and_b32_e32 v149, 0xffff0000, v199
	v_lshlrev_b32_e32 v150, 16, v200
	v_and_b32_e32 v151, 0xffff0000, v200
	v_lshlrev_b32_e32 v152, 16, v201
	v_and_b32_e32 v153, 0xffff0000, v201
	v_pk_mul_f32 v[56:57], v[56:57], v[146:147]
	v_pk_mul_f32 v[58:59], v[58:59], v[148:149]
	v_pk_mul_f32 v[52:53], v[52:53], v[150:151]
	v_pk_mul_f32 v[54:55], v[54:55], v[152:153]
	v_cvt_pk_bf16_f32 v198, v56, v57
	v_cvt_pk_bf16_f32 v199, v58, v59
	v_cvt_pk_bf16_f32 v200, v52, v53
	v_cvt_pk_bf16_f32 v201, v54, v55
	s_add_u32 s10, s4, 0x40000
	s_addc_u32 s11, s5, 0
	global_store_dwordx4 v144, v[198:201], s[10:11]
	s_waitcnt vmcnt(15)
	v_lshlrev_b32_e32 v146, 16, v202
	v_and_b32_e32 v147, 0xffff0000, v202
	v_lshlrev_b32_e32 v148, 16, v203
	v_and_b32_e32 v149, 0xffff0000, v203
	v_lshlrev_b32_e32 v150, 16, v204
	v_and_b32_e32 v151, 0xffff0000, v204
	v_lshlrev_b32_e32 v152, 16, v205
	v_and_b32_e32 v153, 0xffff0000, v205
	v_pk_mul_f32 v[24:25], v[24:25], v[146:147]
	v_pk_mul_f32 v[26:27], v[26:27], v[148:149]
	v_pk_mul_f32 v[20:21], v[20:21], v[150:151]
	v_pk_mul_f32 v[22:23], v[22:23], v[152:153]
	v_cvt_pk_bf16_f32 v202, v24, v25
	v_cvt_pk_bf16_f32 v203, v26, v27
	v_cvt_pk_bf16_f32 v204, v20, v21
	v_cvt_pk_bf16_f32 v205, v22, v23
	global_store_dwordx4 v144, v[202:205], s[10:11] offset:256
	s_waitcnt vmcnt(15)
	v_lshlrev_b32_e32 v146, 16, v206
	v_and_b32_e32 v147, 0xffff0000, v206
	v_lshlrev_b32_e32 v148, 16, v207
	v_and_b32_e32 v149, 0xffff0000, v207
	v_lshlrev_b32_e32 v150, 16, v208
	v_and_b32_e32 v151, 0xffff0000, v208
	v_lshlrev_b32_e32 v152, 16, v209
	v_and_b32_e32 v153, 0xffff0000, v209
	v_pk_mul_f32 v[48:49], v[48:49], v[146:147]
	v_pk_mul_f32 v[50:51], v[50:51], v[148:149]
	v_pk_mul_f32 v[44:45], v[44:45], v[150:151]
	v_pk_mul_f32 v[46:47], v[46:47], v[152:153]
	v_cvt_pk_bf16_f32 v206, v48, v49
	v_cvt_pk_bf16_f32 v207, v50, v51
	v_cvt_pk_bf16_f32 v208, v44, v45
	v_cvt_pk_bf16_f32 v209, v46, v47
	s_add_u32 s10, s4, 0x48000
	s_addc_u32 s11, s5, 0
	global_store_dwordx4 v144, v[206:209], s[10:11]
	s_waitcnt vmcnt(15)
	v_lshlrev_b32_e32 v146, 16, v210
	v_and_b32_e32 v147, 0xffff0000, v210
	v_lshlrev_b32_e32 v148, 16, v211
	v_and_b32_e32 v149, 0xffff0000, v211
	v_lshlrev_b32_e32 v150, 16, v212
	v_and_b32_e32 v151, 0xffff0000, v212
	v_lshlrev_b32_e32 v152, 16, v213
	v_and_b32_e32 v153, 0xffff0000, v213
	v_pk_mul_f32 v[16:17], v[16:17], v[146:147]
	v_pk_mul_f32 v[18:19], v[18:19], v[148:149]
	v_pk_mul_f32 v[12:13], v[12:13], v[150:151]
	v_pk_mul_f32 v[14:15], v[14:15], v[152:153]
	v_cvt_pk_bf16_f32 v210, v16, v17
	v_cvt_pk_bf16_f32 v211, v18, v19
	v_cvt_pk_bf16_f32 v212, v12, v13
	v_cvt_pk_bf16_f32 v213, v14, v15
	global_store_dwordx4 v144, v[210:213], s[10:11] offset:256
	s_waitcnt vmcnt(15)
	v_lshlrev_b32_e32 v146, 16, v226
	v_and_b32_e32 v147, 0xffff0000, v226
	v_lshlrev_b32_e32 v148, 16, v227
	v_and_b32_e32 v149, 0xffff0000, v227
	v_lshlrev_b32_e32 v150, 16, v228
	v_and_b32_e32 v151, 0xffff0000, v228
	v_lshlrev_b32_e32 v152, 16, v229
	v_and_b32_e32 v153, 0xffff0000, v229
	v_pk_mul_f32 v[40:41], v[40:41], v[146:147]
	v_pk_mul_f32 v[42:43], v[42:43], v[148:149]
	v_pk_mul_f32 v[36:37], v[36:37], v[150:151]
	v_pk_mul_f32 v[38:39], v[38:39], v[152:153]
	v_cvt_pk_bf16_f32 v226, v40, v41
	v_cvt_pk_bf16_f32 v227, v42, v43
	v_cvt_pk_bf16_f32 v228, v36, v37
	v_cvt_pk_bf16_f32 v229, v38, v39
	s_add_u32 s10, s4, 0x50000
	s_addc_u32 s11, s5, 0
	global_store_dwordx4 v144, v[226:229], s[10:11]
	s_waitcnt vmcnt(15)
	v_lshlrev_b32_e32 v146, 16, v232
	v_and_b32_e32 v147, 0xffff0000, v232
	v_lshlrev_b32_e32 v148, 16, v233
	v_and_b32_e32 v149, 0xffff0000, v233
	v_lshlrev_b32_e32 v150, 16, v234
	v_and_b32_e32 v151, 0xffff0000, v234
	v_lshlrev_b32_e32 v152, 16, v235
	v_and_b32_e32 v153, 0xffff0000, v235
	v_pk_mul_f32 v[8:9], v[8:9], v[146:147]
	v_pk_mul_f32 v[10:11], v[10:11], v[148:149]
	v_pk_mul_f32 v[4:5], v[4:5], v[150:151]
	v_pk_mul_f32 v[6:7], v[6:7], v[152:153]
	v_cvt_pk_bf16_f32 v232, v8, v9
	v_cvt_pk_bf16_f32 v233, v10, v11
	v_cvt_pk_bf16_f32 v234, v4, v5
	v_cvt_pk_bf16_f32 v235, v6, v7
	global_store_dwordx4 v144, v[232:235], s[10:11] offset:256
	s_waitcnt vmcnt(15)
	v_lshlrev_b32_e32 v146, 16, v236
	v_and_b32_e32 v147, 0xffff0000, v236
	v_lshlrev_b32_e32 v148, 16, v237
	v_and_b32_e32 v149, 0xffff0000, v237
	v_lshlrev_b32_e32 v150, 16, v238
	v_and_b32_e32 v151, 0xffff0000, v238
	v_lshlrev_b32_e32 v152, 16, v239
	v_and_b32_e32 v153, 0xffff0000, v239
	v_pk_mul_f32 v[32:33], v[32:33], v[146:147]
	v_pk_mul_f32 v[34:35], v[34:35], v[148:149]
	v_pk_mul_f32 v[28:29], v[28:29], v[150:151]
	v_pk_mul_f32 v[30:31], v[30:31], v[152:153]
	v_cvt_pk_bf16_f32 v236, v32, v33
	v_cvt_pk_bf16_f32 v237, v34, v35
	v_cvt_pk_bf16_f32 v238, v28, v29
	v_cvt_pk_bf16_f32 v239, v30, v31
	s_add_u32 s10, s4, 0x58000
	s_addc_u32 s11, s5, 0
	global_store_dwordx4 v144, v[236:239], s[10:11]
	s_waitcnt vmcnt(15)
	v_lshlrev_b32_e32 v146, 16, v240
	v_and_b32_e32 v147, 0xffff0000, v240
	v_lshlrev_b32_e32 v148, 16, v241
	v_and_b32_e32 v149, 0xffff0000, v241
	v_lshlrev_b32_e32 v150, 16, v242
	v_and_b32_e32 v151, 0xffff0000, v242
	v_lshlrev_b32_e32 v152, 16, v243
	v_and_b32_e32 v153, 0xffff0000, v243
	v_pk_mul_f32 v[124:125], v[124:125], v[146:147]
	v_pk_mul_f32 v[126:127], v[126:127], v[148:149]
	v_pk_mul_f32 v[128:129], v[128:129], v[150:151]
	v_pk_mul_f32 v[130:131], v[130:131], v[152:153]
	v_cvt_pk_bf16_f32 v240, v124, v125
	v_cvt_pk_bf16_f32 v241, v126, v127
	v_cvt_pk_bf16_f32 v242, v128, v129
	v_cvt_pk_bf16_f32 v243, v130, v131
	global_store_dwordx4 v144, v[240:243], s[10:11] offset:256
